# phase 5 (short context-segment scan): every workgroup takes two prep pairs instead of 3 for prep-only and 1 for scan workgroups
# speedup vs baseline: 1.0082x; 1.0032x over previous
.LBB0_551:
	v_readlane_b32 s0, v255, 17
	v_readlane_b32 s2, v250, 0
	v_readlane_b32 s22, v254, 38
	s_nop 3
	s_add_i32 s1, s0, 1
	v_writelane_b32 v255, s1, 17
	s_cmp_lt_u32 s2, 0x80
	s_cbranch_scc1 .Lps_b
	s_lshl_b32 s1, s0, 7
	s_add_i32 s1, s1, s2
	s_addk_i32 s1, 0xff80
	s_cmp_eq_u32 s22, 6
	s_cselect_b32 s23, 2, 3
	s_cmp_lt_u32 s0, s23
	s_branch .Lps_j
.Lps_b:
	s_cmp_eq_u32 s22, 6
	s_cbranch_scc1 .Lps_b5
	s_add_i32 s1, s2, 0x180
	s_cmp_lt_u32 s0, 1
	s_branch .Lps_j
.Lps_b5:
	s_lshl_b32 s1, s0, 7
	s_add_i32 s1, s1, s2
	s_addk_i32 s1, 0x100
	s_cmp_lt_u32 s0, 2
